# attention preamble: lambda dot-product loop unrolled, its 32 uniform loads issued up front
# baseline (speedup 1.0000x reference)
.LBB0_627:
	s_mov_b32 s56, s15
	s_mov_b32 s57, s18
	s_mov_b32 s58, s19
	s_mov_b32 s59, s28
	global_load_dwordx4 v[4:7], v3, s[6:7] offset:16
	global_load_dwordx4 v[8:11], v3, s[6:7]
	global_load_dwordx4 v[12:15], v3, s[8:9] offset:16
	global_load_dwordx4 v[16:19], v3, s[8:9]
	global_load_dwordx4 v[20:23], v3, s[56:57] offset:16
	global_load_dwordx4 v[24:27], v3, s[56:57]
	global_load_dwordx4 v[28:31], v3, s[58:59] offset:16
	global_load_dwordx4 v[32:35], v3, s[58:59]
	global_load_dwordx4 v[44:47], v3, s[6:7] offset:48
	global_load_dwordx4 v[48:51], v3, s[6:7] offset:32
	global_load_dwordx4 v[52:55], v3, s[8:9] offset:48
	global_load_dwordx4 v[56:59], v3, s[8:9] offset:32
	global_load_dwordx4 v[60:63], v3, s[56:57] offset:48
	global_load_dwordx4 v[64:67], v3, s[56:57] offset:32
	global_load_dwordx4 v[68:71], v3, s[58:59] offset:48
	global_load_dwordx4 v[72:75], v3, s[58:59] offset:32
	global_load_dwordx4 v[84:87], v3, s[6:7] offset:80
	global_load_dwordx4 v[88:91], v3, s[6:7] offset:64
	global_load_dwordx4 v[92:95], v3, s[8:9] offset:80
	global_load_dwordx4 v[96:99], v3, s[8:9] offset:64
	global_load_dwordx4 v[100:103], v3, s[56:57] offset:80
	global_load_dwordx4 v[104:107], v3, s[56:57] offset:64
	global_load_dwordx4 v[108:111], v3, s[58:59] offset:80
	global_load_dwordx4 v[112:115], v3, s[58:59] offset:64
	global_load_dwordx4 v[124:127], v3, s[6:7] offset:112
	global_load_dwordx4 v[128:131], v3, s[6:7] offset:96
	global_load_dwordx4 v[132:135], v3, s[8:9] offset:112
	global_load_dwordx4 v[136:139], v3, s[8:9] offset:96
	global_load_dwordx4 v[140:143], v3, s[56:57] offset:112
	global_load_dwordx4 v[144:147], v3, s[56:57] offset:96
	global_load_dwordx4 v[148:151], v3, s[58:59] offset:112
	global_load_dwordx4 v[152:155], v3, s[58:59] offset:96
	s_waitcnt vmcnt(30)
	v_mov_b32_e32 v36, v8
	s_waitcnt vmcnt(28)
	v_mov_b32_e32 v38, v16
	v_mov_b32_e32 v16, v10
	v_mov_b32_e32 v10, v4
	s_waitcnt vmcnt(26)
	v_mov_b32_e32 v37, v24
	v_mov_b32_e32 v24, v9
	s_waitcnt vmcnt(24)
	v_mov_b32_e32 v39, v32
	v_pk_fma_f32 v[36:37], v[36:37], v[38:39], v[160:161]
	v_mov_b32_e32 v32, v17
	v_pk_fma_f32 v[8:9], v[24:25], v[32:33], v[36:37]
	v_mov_b32_e32 v17, v26
	v_mov_b32_e32 v24, v18
	v_mov_b32_e32 v25, v34
	v_pk_fma_f32 v[8:9], v[16:17], v[24:25], v[8:9]
	v_mov_b32_e32 v26, v11
	v_mov_b32_e32 v34, v19
	v_pk_fma_f32 v[8:9], v[26:27], v[34:35], v[8:9]
	v_mov_b32_e32 v11, v20
	v_mov_b32_e32 v16, v12
	v_mov_b32_e32 v17, v28
	v_pk_fma_f32 v[8:9], v[10:11], v[16:17], v[8:9]
	v_mov_b32_e32 v20, v5
	v_mov_b32_e32 v28, v13
	v_pk_fma_f32 v[4:5], v[20:21], v[28:29], v[8:9]
	v_mov_b32_e32 v8, v6
	v_mov_b32_e32 v9, v22
	v_mov_b32_e32 v10, v14
	v_mov_b32_e32 v11, v30
	v_pk_fma_f32 v[4:5], v[8:9], v[10:11], v[4:5]
	v_mov_b32_e32 v22, v7
	v_mov_b32_e32 v30, v15
	v_pk_fma_f32 v[160:161], v[22:23], v[30:31], v[4:5]
	s_waitcnt vmcnt(22)
	v_mov_b32_e32 v76, v48
	s_waitcnt vmcnt(20)
	v_mov_b32_e32 v78, v56
	v_mov_b32_e32 v56, v50
	v_mov_b32_e32 v50, v44
	s_waitcnt vmcnt(18)
	v_mov_b32_e32 v77, v64
	v_mov_b32_e32 v64, v49
	s_waitcnt vmcnt(16)
	v_mov_b32_e32 v79, v72
	v_pk_fma_f32 v[76:77], v[76:77], v[78:79], v[160:161]
	v_mov_b32_e32 v72, v57
	v_pk_fma_f32 v[48:49], v[64:65], v[72:73], v[76:77]
	v_mov_b32_e32 v57, v66
	v_mov_b32_e32 v64, v58
	v_mov_b32_e32 v65, v74
	v_pk_fma_f32 v[48:49], v[56:57], v[64:65], v[48:49]
	v_mov_b32_e32 v66, v51
	v_mov_b32_e32 v74, v59
	v_pk_fma_f32 v[48:49], v[66:67], v[74:75], v[48:49]
	v_mov_b32_e32 v51, v60
	v_mov_b32_e32 v56, v52
	v_mov_b32_e32 v57, v68
	v_pk_fma_f32 v[48:49], v[50:51], v[56:57], v[48:49]
	v_mov_b32_e32 v60, v45
	v_mov_b32_e32 v68, v53
	v_pk_fma_f32 v[44:45], v[60:61], v[68:69], v[48:49]
	v_mov_b32_e32 v48, v46
	v_mov_b32_e32 v49, v62
	v_mov_b32_e32 v50, v54
	v_mov_b32_e32 v51, v70
	v_pk_fma_f32 v[44:45], v[48:49], v[50:51], v[44:45]
	v_mov_b32_e32 v62, v47
	v_mov_b32_e32 v70, v55
	v_pk_fma_f32 v[160:161], v[62:63], v[70:71], v[44:45]
	s_waitcnt vmcnt(14)
	v_mov_b32_e32 v116, v88
	s_waitcnt vmcnt(12)
	v_mov_b32_e32 v118, v96
	v_mov_b32_e32 v96, v90
	v_mov_b32_e32 v90, v84
	s_waitcnt vmcnt(10)
	v_mov_b32_e32 v117, v104
	v_mov_b32_e32 v104, v89
	s_waitcnt vmcnt(8)
	v_mov_b32_e32 v119, v112
	v_pk_fma_f32 v[116:117], v[116:117], v[118:119], v[160:161]
	v_mov_b32_e32 v112, v97
	v_pk_fma_f32 v[88:89], v[104:105], v[112:113], v[116:117]
	v_mov_b32_e32 v97, v106
	v_mov_b32_e32 v104, v98
	v_mov_b32_e32 v105, v114
	v_pk_fma_f32 v[88:89], v[96:97], v[104:105], v[88:89]
	v_mov_b32_e32 v106, v91
	v_mov_b32_e32 v114, v99
	v_pk_fma_f32 v[88:89], v[106:107], v[114:115], v[88:89]
	v_mov_b32_e32 v91, v100
	v_mov_b32_e32 v96, v92
	v_mov_b32_e32 v97, v108
	v_pk_fma_f32 v[88:89], v[90:91], v[96:97], v[88:89]
	v_mov_b32_e32 v100, v85
	v_mov_b32_e32 v108, v93
	v_pk_fma_f32 v[84:85], v[100:101], v[108:109], v[88:89]
	v_mov_b32_e32 v88, v86
	v_mov_b32_e32 v89, v102
	v_mov_b32_e32 v90, v94
	v_mov_b32_e32 v91, v110
	v_pk_fma_f32 v[84:85], v[88:89], v[90:91], v[84:85]
	v_mov_b32_e32 v102, v87
	v_mov_b32_e32 v110, v95
	v_pk_fma_f32 v[160:161], v[102:103], v[110:111], v[84:85]
	s_waitcnt vmcnt(6)
	v_mov_b32_e32 v156, v128
	s_waitcnt vmcnt(4)
	v_mov_b32_e32 v158, v136
	v_mov_b32_e32 v136, v130
	v_mov_b32_e32 v130, v124
	s_waitcnt vmcnt(2)
	v_mov_b32_e32 v157, v144
	v_mov_b32_e32 v144, v129
	s_waitcnt vmcnt(0)
	v_mov_b32_e32 v159, v152
	v_pk_fma_f32 v[156:157], v[156:157], v[158:159], v[160:161]
	v_mov_b32_e32 v152, v137
	v_pk_fma_f32 v[128:129], v[144:145], v[152:153], v[156:157]
	v_mov_b32_e32 v137, v146
	v_mov_b32_e32 v144, v138
	v_mov_b32_e32 v145, v154
	v_pk_fma_f32 v[128:129], v[136:137], v[144:145], v[128:129]
	v_mov_b32_e32 v146, v131
	v_mov_b32_e32 v154, v139
	v_pk_fma_f32 v[128:129], v[146:147], v[154:155], v[128:129]
	v_mov_b32_e32 v131, v140
	v_mov_b32_e32 v136, v132
	v_mov_b32_e32 v137, v148
	v_pk_fma_f32 v[128:129], v[130:131], v[136:137], v[128:129]
	v_mov_b32_e32 v140, v125
	v_mov_b32_e32 v148, v133
	v_pk_fma_f32 v[124:125], v[140:141], v[148:149], v[128:129]
	v_mov_b32_e32 v128, v126
	v_mov_b32_e32 v129, v142
	v_mov_b32_e32 v130, v134
	v_mov_b32_e32 v131, v150
	v_pk_fma_f32 v[124:125], v[128:129], v[130:131], v[124:125]
	v_mov_b32_e32 v142, v127
	v_mov_b32_e32 v150, v135
	v_pk_fma_f32 v[160:161], v[142:143], v[150:151], v[124:125]
	s_ashr_i32 s4, s14, 5
	s_and_b32 s54, s14, 7
	s_add_u32 s6, s26, 0x6b00000
	s_addc_u32 s7, s27, 0
	s_lshl_b32 s8, s54, 2
	v_readlane_b32 s9, v254, 58
	v_ashrrev_i32_e32 v25, 5, v163
	s_or_b32 s15, s8, s9
	v_lshlrev_b32_e32 v4, 3, v25
	s_ashr_i32 s5, s4, 31
	v_and_b32_e32 v24, 31, v163
	s_xor_b32 s66, s15, 63
	v_ashrrev_i32_e32 v5, 31, v4
	s_lshl_b64 s[4:5], s[4:5], 11
	v_lshl_or_b32 v6, s66, 5, v24
	v_lshlrev_b64 v[10:11], 1, v[4:5]
	v_lshl_or_b32 v5, s15, 5, v24
	v_or_b32_e32 v158, s4, v6
	v_mov_b64_e32 v[6:7], s[6:7]
	s_movk_i32 s18, 0x1200
	v_or_b32_e32 v156, s4, v5
	s_bfe_u32 s56, s14, 0x20003
	v_mad_u64_u32 v[8:9], s[8:9], v158, s18, v[6:7]
	v_readlane_b32 s28, v255, 4
	v_mad_u64_u32 v[6:7], s[8:9], v156, s18, v[6:7]
	v_mad_i32_i24 v9, s5, v222, v9
	s_lshl_b32 s34, s56, 7
	v_readlane_b32 s29, v255, 5
	v_mad_i32_i24 v7, s5, v222, v7
	v_lshl_add_u64 v[8:9], v[8:9], 0, s[34:35]
	s_mov_b32 s29, s35
	v_lshl_add_u64 v[6:7], v[6:7], 0, s[34:35]
	v_lshl_add_u64 v[8:9], v[8:9], 0, s[28:29]
	v_lshl_add_u64 v[6:7], v[6:7], 0, s[28:29]
	v_lshl_add_u64 v[8:9], v[8:9], 0, v[10:11]
	v_lshl_add_u64 v[6:7], v[6:7], 0, v[10:11]
	global_load_dwordx4 v[100:103], v[8:9], off offset:3584
	global_load_dwordx4 v[104:107], v[8:9], off offset:3616
	global_load_dwordx4 v[108:111], v[6:7], off offset:3584
	global_load_dwordx4 v[112:115], v[6:7], off offset:3616
	s_mov_b32 s8, s28
	v_writelane_b32 v255, s8, 4
	s_lshl_b32 s55, s56, 6
	s_mov_b32 s34, s35
	v_writelane_b32 v255, s9, 5
	s_load_dwordx2 s[8:9], s[22:23], 0x78
	v_mov_b32_e32 v159, s5
	v_mov_b32_e32 v157, s5
	s_mov_b32 s57, 0
	s_mov_b64 s[18:19], 0
	s_waitcnt lgkmcnt(0)
	s_add_u32 s58, s8, s0
	s_addc_u32 s59, s9, s1
	v_mov_b64_e32 v[12:13], s[34:35]
